# SSM pass 1: recurrence as in-place scalar v_fmac on the MFMA outputs (no pairing moves / packed ops)
# baseline (speedup 1.0000x reference)
.LBB0_495:
	v_mfma_f32_32x32x16_bf16 v[50:65], v[34:37], v[78:81], 0
	s_add_i32 s78, s78, 1
	v_lshl_add_u64 v[110:111], v[110:111], 0, s[70:71]
	s_cmp_eq_u32 s78, 16
	v_mfma_f32_32x32x16_bf16 v[2:17], v[34:37], v[66:69], 0
	v_mfma_f32_32x32x16_bf16 v[18:33], v[34:37], v[70:73], 0
	v_mfma_f32_32x32x16_bf16 v[34:49], v[34:37], v[74:77], 0
	v_xor_b32_e32 v254, 0x80000000, v156
	v_xor_b32_e32 v255, 0x80000000, v157
	s_nop 9
	v_fmac_f32_e32 v50, v160, v112
	v_fmac_f32_e32 v2, v161, v113
	v_fmac_f32_e32 v18, v160, v114
	v_fmac_f32_e32 v34, v161, v115
	v_fmac_f32_e32 v50, v254, v114
	v_fmac_f32_e32 v2, v255, v115
	v_fmac_f32_e32 v18, v156, v112
	v_fmac_f32_e32 v34, v157, v113
	v_fmac_f32_e32 v51, v160, v50
	v_fmac_f32_e32 v3, v161, v2
	v_fmac_f32_e32 v19, v160, v18
	v_fmac_f32_e32 v35, v161, v34
	v_fmac_f32_e32 v51, v254, v18
	v_fmac_f32_e32 v3, v255, v34
	v_fmac_f32_e32 v19, v156, v50
	v_fmac_f32_e32 v35, v157, v2
	v_fmac_f32_e32 v52, v160, v51
	v_fmac_f32_e32 v4, v161, v3
	v_fmac_f32_e32 v20, v160, v19
	v_fmac_f32_e32 v36, v161, v35
	v_fmac_f32_e32 v52, v254, v19
	v_fmac_f32_e32 v4, v255, v35
	v_fmac_f32_e32 v20, v156, v51
	v_fmac_f32_e32 v36, v157, v3
	v_fmac_f32_e32 v53, v160, v52
	v_fmac_f32_e32 v5, v161, v4
	v_fmac_f32_e32 v21, v160, v20
	v_fmac_f32_e32 v37, v161, v36
	v_fmac_f32_e32 v53, v254, v20
	v_fmac_f32_e32 v5, v255, v36
	v_fmac_f32_e32 v21, v156, v52
	v_fmac_f32_e32 v37, v157, v4
	v_fmac_f32_e32 v54, v160, v53
	v_fmac_f32_e32 v6, v161, v5
	v_fmac_f32_e32 v22, v160, v21
	v_fmac_f32_e32 v38, v161, v37
	v_fmac_f32_e32 v54, v254, v21
	v_fmac_f32_e32 v6, v255, v37
	v_fmac_f32_e32 v22, v156, v53
	v_fmac_f32_e32 v38, v157, v5
	s_waitcnt vmcnt(1)
	v_mov_b64_e32 v[34:35], v[86:87]
	v_mov_b64_e32 v[36:37], v[88:89]
	v_mov_b64_e32 v[88:89], v[84:85]
	v_mov_b64_e32 v[86:87], v[82:83]
	v_mov_b64_e32 v[82:83], v[90:91]
	v_mov_b64_e32 v[84:85], v[92:93]
	v_fmac_f32_e32 v55, v160, v54
	v_fmac_f32_e32 v7, v161, v6
	v_fmac_f32_e32 v23, v160, v22
	v_fmac_f32_e32 v39, v161, v38
	v_fmac_f32_e32 v55, v254, v22
	v_fmac_f32_e32 v7, v255, v38
	v_fmac_f32_e32 v23, v156, v54
	v_fmac_f32_e32 v39, v157, v6
	v_fmac_f32_e32 v56, v160, v55
	v_fmac_f32_e32 v8, v161, v7
	v_fmac_f32_e32 v24, v160, v23
	v_fmac_f32_e32 v40, v161, v39
	v_fmac_f32_e32 v56, v254, v23
	v_fmac_f32_e32 v8, v255, v39
	v_fmac_f32_e32 v24, v156, v55
	v_fmac_f32_e32 v40, v157, v7
	v_fmac_f32_e32 v57, v160, v56
	v_fmac_f32_e32 v9, v161, v8
	v_fmac_f32_e32 v25, v160, v24
	v_fmac_f32_e32 v41, v161, v40
	v_fmac_f32_e32 v57, v254, v24
	v_fmac_f32_e32 v9, v255, v40
	v_fmac_f32_e32 v25, v156, v56
	v_fmac_f32_e32 v41, v157, v8
	v_fmac_f32_e32 v58, v160, v57
	v_fmac_f32_e32 v10, v161, v9
	v_fmac_f32_e32 v26, v160, v25
	v_fmac_f32_e32 v42, v161, v41
	v_fmac_f32_e32 v58, v254, v25
	v_fmac_f32_e32 v10, v255, v41
	v_fmac_f32_e32 v26, v156, v57
	v_fmac_f32_e32 v42, v157, v9
	v_fmac_f32_e32 v59, v160, v58
	v_fmac_f32_e32 v11, v161, v10
	v_fmac_f32_e32 v27, v160, v26
	v_fmac_f32_e32 v43, v161, v42
	v_fmac_f32_e32 v59, v254, v26
	v_fmac_f32_e32 v11, v255, v42
	v_fmac_f32_e32 v27, v156, v58
	v_fmac_f32_e32 v43, v157, v10
	v_fmac_f32_e32 v60, v160, v59
	v_fmac_f32_e32 v12, v161, v11
	v_fmac_f32_e32 v28, v160, v27
	v_fmac_f32_e32 v44, v161, v43
	v_fmac_f32_e32 v60, v254, v27
	v_fmac_f32_e32 v12, v255, v43
	v_fmac_f32_e32 v28, v156, v59
	v_fmac_f32_e32 v44, v157, v11
	v_fmac_f32_e32 v61, v160, v60
	v_fmac_f32_e32 v13, v161, v12
	v_fmac_f32_e32 v29, v160, v28
	v_fmac_f32_e32 v45, v161, v44
	v_fmac_f32_e32 v61, v254, v28
	v_fmac_f32_e32 v13, v255, v44
	v_fmac_f32_e32 v29, v156, v60
	v_fmac_f32_e32 v45, v157, v12
	v_fmac_f32_e32 v62, v160, v61
	v_fmac_f32_e32 v14, v161, v13
	v_fmac_f32_e32 v30, v160, v29
	v_fmac_f32_e32 v46, v161, v45
	v_fmac_f32_e32 v62, v254, v29
	v_fmac_f32_e32 v14, v255, v45
	v_fmac_f32_e32 v30, v156, v61
	v_fmac_f32_e32 v46, v157, v13
	v_fmac_f32_e32 v63, v160, v62
	v_fmac_f32_e32 v15, v161, v14
	v_fmac_f32_e32 v31, v160, v30
	v_fmac_f32_e32 v47, v161, v46
	v_fmac_f32_e32 v63, v254, v30
	v_fmac_f32_e32 v15, v255, v46
	v_fmac_f32_e32 v31, v156, v62
	v_fmac_f32_e32 v47, v157, v14
	v_fmac_f32_e32 v64, v160, v63
	v_fmac_f32_e32 v16, v161, v15
	v_fmac_f32_e32 v32, v160, v31
	v_fmac_f32_e32 v48, v161, v47
	v_fmac_f32_e32 v64, v254, v31
	v_fmac_f32_e32 v16, v255, v47
	v_fmac_f32_e32 v32, v156, v63
	v_fmac_f32_e32 v48, v157, v15
	v_fmac_f32_e32 v65, v160, v64
	v_fmac_f32_e32 v17, v161, v16
	v_fmac_f32_e32 v33, v160, v32
	v_fmac_f32_e32 v49, v161, v48
	v_fmac_f32_e32 v65, v254, v32
	v_fmac_f32_e32 v17, v255, v48
	v_fmac_f32_e32 v33, v156, v64
	v_fmac_f32_e32 v49, v157, v16
	s_waitcnt vmcnt(0)
	v_mov_b64_e32 v[90:91], v[94:95]
	v_mov_b64_e32 v[92:93], v[96:97]
	v_mov_b32_e32 v112, v65
	v_mov_b32_e32 v113, v17
	v_mov_b32_e32 v114, v33
	v_mov_b32_e32 v115, v49
	s_cbranch_scc1 .LBB0_498
